# v32 + non-temporal stores for the final output rows (never re-read)
# speedup vs baseline: 1.0127x; 1.0016x over previous
.LBB0_915:
	s_or_b64 exec, exec, s[20:21]
	v_lshlrev_b32_e32 v55, 16, v45
	v_lshlrev_b32_e32 v54, 16, v44
	v_and_b32_e32 v45, 0xffff0000, v45
	v_and_b32_e32 v44, 0xffff0000, v44
	v_lshlrev_b32_e32 v64, 16, v30
	v_and_b32_e32 v57, 0xffff0000, v30
	v_lshlrev_b32_e32 v66, 16, v31
	v_and_b32_e32 v67, 0xffff0000, v31
	v_pk_mul_f32 v[30:31], v[44:45], v[44:45]
	v_lshlrev_b32_e32 v59, 16, v43
	v_lshlrev_b32_e32 v58, 16, v42
	v_and_b32_e32 v43, 0xffff0000, v43
	v_and_b32_e32 v42, 0xffff0000, v42
	v_pk_fma_f32 v[30:31], v[54:55], v[54:55], v[30:31]
	v_lshlrev_b32_e32 v60, 16, v32
	v_and_b32_e32 v61, 0xffff0000, v32
	v_lshlrev_b32_e32 v62, 16, v33
	v_and_b32_e32 v63, 0xffff0000, v33
	v_pk_add_f32 v[30:31], v[30:31], v[30:31] op_sel_hi:[0,1]
	v_pk_mul_f32 v[32:33], v[42:43], v[42:43]
	v_mul_f32_e32 v65, v60, v60
	v_pk_fma_f32 v[32:33], v[58:59], v[58:59], v[32:33]
	v_mul_f32_e32 v69, v61, v61
	v_mul_f32_e32 v30, v62, v62
	v_mov_b32_e32 v68, v64
	v_pk_add_f32 v[32:33], v[32:33], v[32:33] op_sel_hi:[0,1]
	v_pk_fma_f32 v[70:71], v[62:63], v[62:63], v[30:31] op_sel_hi:[1,1,0]
	v_pk_add_f32 v[68:69], v[64:65], v[68:69]
	v_mul_f32_e32 v70, v57, v57
	v_mul_f32_e32 v30, v66, v66
	v_mul_f32_e32 v32, v67, v67
	v_mul_f32_e32 v72, v64, v64
	v_mov_b32_e32 v73, v69
	v_pk_add_f32 v[68:69], v[72:73], v[70:71]
	v_pk_add_f32 v[30:31], v[30:31], v[32:33]
	v_mov_b32_e32 v65, v57
	v_pk_add_f32 v[30:31], v[68:69], v[30:31]
	s_nop 0
	v_add_f32_e32 v29, v30, v31
	v_mov_b32_e32 v30, v181
	v_mov_b32_e32 v31, v44
	v_add_f32_dpp v29, v29, v29 row_shr:1 row_mask:0xf bank_mask:0xf bound_ctrl:1
	v_mov_b32_e32 v44, v55
	s_nop 0
	v_add_f32_dpp v29, v29, v29 row_shr:2 row_mask:0xf bank_mask:0xf bound_ctrl:1
	s_nop 1
	v_add_f32_dpp v29, v29, v29 row_shr:4 row_mask:0xf bank_mask:0xf bound_ctrl:1
	s_nop 1
	v_add_f32_dpp v29, v29, v29 row_shr:8 row_mask:0xf bank_mask:0xf bound_ctrl:1
	s_nop 1
	v_mov_b32_dpp v30, v29 row_bcast:15 row_mask:0xa bank_mask:0xf
	v_add_f32_e32 v29, v29, v30
	v_mov_b32_e32 v30, v181
	s_nop 1
	v_mov_b32_dpp v30, v29 row_bcast:31 row_mask:0xc bank_mask:0xf
	v_add_f32_e32 v29, v29, v30
	v_mov_b32_e32 v30, v54
	v_readlane_b32 s0, v29, 63
	s_nop 1
	v_fma_f32 v29, s0, v247, v237
	v_rsq_f32_e32 v68, v29
	v_ashrrev_i32_e32 v29, 31, v28
	v_lshlrev_b64 v[70:71], 12, v[28:29]
	v_pk_mul_f32 v[30:31], v[68:69], v[30:31] op_sel_hi:[0,1]
	v_pk_mul_f32 v[32:33], v[68:69], v[44:45] op_sel_hi:[0,1]
	v_pk_mul_f32 v[32:33], v[6:7], v[32:33]
	v_pk_mul_f32 v[30:31], v[4:5], v[30:31]
	v_lshl_add_u64 v[44:45], v[22:23], 0, v[70:71]
	global_store_dwordx4 v[44:45], v[30:33], off nt
	s_nop 1
	v_mov_b32_e32 v30, v58
	v_mov_b32_e32 v31, v42
	v_mov_b32_e32 v42, v59
	v_pk_mul_f32 v[30:31], v[68:69], v[30:31] op_sel_hi:[0,1]
	v_pk_mul_f32 v[32:33], v[68:69], v[42:43] op_sel_hi:[0,1]
	v_pk_mul_f32 v[32:33], v[10:11], v[32:33]
	v_pk_mul_f32 v[30:31], v[8:9], v[30:31]
	global_store_dwordx4 v[44:45], v[30:33], off offset:1024 nt
	s_waitcnt vmcnt(4)
	v_mov_b32_e32 v43, v49
	v_mov_b32_e32 v42, v48
	v_pk_mul_f32 v[30:31], v[68:69], v[60:61] op_sel_hi:[0,1]
	v_pk_mul_f32 v[32:33], v[68:69], v[62:63] op_sel_hi:[0,1]
	v_pk_mul_f32 v[32:33], v[14:15], v[32:33]
	v_pk_mul_f32 v[30:31], v[12:13], v[30:31]
	global_store_dwordx4 v[44:45], v[30:33], off offset:2048 nt
	s_nop 1
	v_pk_mul_f32 v[30:31], v[68:69], v[64:65] op_sel_hi:[0,1]
	v_pk_mul_f32 v[32:33], v[68:69], v[66:67] op_sel_hi:[0,1]
	v_pk_mul_f32 v[32:33], v[18:19], v[32:33]
	v_pk_mul_f32 v[30:31], v[16:17], v[30:31]
	global_store_dwordx4 v[44:45], v[30:33], off offset:3072 nt
	v_mov_b32_e32 v45, v47
	v_mov_b32_e32 v44, v46
	s_waitcnt vmcnt(4)
	v_mov_b32_e32 v31, v53
	v_mov_b32_e32 v30, v52
	v_mov_b32_e32 v33, v51
	v_mov_b32_e32 v32, v50

.LBB0_919:
	s_or_b64 exec, exec, s[4:5]
	v_lshlrev_b32_e32 v59, 16, v55
	v_lshlrev_b32_e32 v58, 16, v54
	v_and_b32_e32 v55, 0xffff0000, v55
	v_and_b32_e32 v54, 0xffff0000, v54
	v_lshlrev_b32_e32 v66, 16, v48
	v_and_b32_e32 v29, 0xffff0000, v48
	v_lshlrev_b32_e32 v68, 16, v49
	v_and_b32_e32 v69, 0xffff0000, v49
	v_pk_mul_f32 v[48:49], v[54:55], v[54:55]
	v_lshlrev_b32_e32 v61, 16, v53
	v_lshlrev_b32_e32 v60, 16, v52
	v_and_b32_e32 v53, 0xffff0000, v53
	v_and_b32_e32 v52, 0xffff0000, v52
	v_pk_fma_f32 v[48:49], v[58:59], v[58:59], v[48:49]
	v_lshlrev_b32_e32 v62, 16, v50
	v_and_b32_e32 v63, 0xffff0000, v50
	v_lshlrev_b32_e32 v64, 16, v51
	v_and_b32_e32 v65, 0xffff0000, v51
	v_pk_add_f32 v[48:49], v[48:49], v[48:49] op_sel_hi:[0,1]
	v_pk_mul_f32 v[50:51], v[52:53], v[52:53]
	v_mul_f32_e32 v67, v62, v62
	v_pk_fma_f32 v[50:51], v[60:61], v[60:61], v[50:51]
	v_mul_f32_e32 v71, v63, v63
	v_mul_f32_e32 v48, v64, v64
	v_mov_b32_e32 v70, v66
	v_pk_add_f32 v[50:51], v[50:51], v[50:51] op_sel_hi:[0,1]
	v_pk_fma_f32 v[72:73], v[64:65], v[64:65], v[48:49] op_sel_hi:[1,1,0]
	v_pk_add_f32 v[70:71], v[66:67], v[70:71]
	v_mul_f32_e32 v72, v29, v29
	v_mul_f32_e32 v48, v68, v68
	v_mul_f32_e32 v50, v69, v69
	v_mul_f32_e32 v74, v66, v66
	v_mov_b32_e32 v75, v71
	v_pk_add_f32 v[70:71], v[74:75], v[72:73]
	v_pk_add_f32 v[48:49], v[48:49], v[50:51]
	v_mov_b32_e32 v67, v29
	v_pk_add_f32 v[48:49], v[70:71], v[48:49]
	v_cmp_gt_i32_e64 s[6:7], s70, v28
	v_add_f32_e32 v47, v48, v49
	v_mov_b32_e32 v48, v181
	v_mov_b32_e32 v49, v54
	v_add_f32_dpp v47, v47, v47 row_shr:1 row_mask:0xf bank_mask:0xf bound_ctrl:1
	v_mov_b32_e32 v54, v59
	s_nop 0
	v_add_f32_dpp v47, v47, v47 row_shr:2 row_mask:0xf bank_mask:0xf bound_ctrl:1
	s_nop 1
	v_add_f32_dpp v47, v47, v47 row_shr:4 row_mask:0xf bank_mask:0xf bound_ctrl:1
	s_nop 1
	v_add_f32_dpp v47, v47, v47 row_shr:8 row_mask:0xf bank_mask:0xf bound_ctrl:1
	s_nop 1
	v_mov_b32_dpp v48, v47 row_bcast:15 row_mask:0xa bank_mask:0xf
	v_add_f32_e32 v47, v47, v48
	v_mov_b32_e32 v48, v181
	s_nop 1
	v_mov_b32_dpp v48, v47 row_bcast:31 row_mask:0xc bank_mask:0xf
	v_add_f32_e32 v47, v47, v48
	v_mov_b32_e32 v48, v58
	v_readlane_b32 s0, v47, 63
	s_nop 1
	v_fma_f32 v47, s0, v247, v237
	v_rsq_f32_e32 v70, v47
	s_nop 0
	v_pk_mul_f32 v[48:49], v[70:71], v[48:49] op_sel_hi:[0,1]
	v_pk_mul_f32 v[50:51], v[70:71], v[54:55] op_sel_hi:[0,1]
	v_pk_mul_f32 v[50:51], v[6:7], v[50:51]
	v_pk_mul_f32 v[48:49], v[4:5], v[48:49]
	v_lshl_add_u64 v[54:55], s[10:11], 0, v[26:27]
	global_store_dwordx4 v[54:55], v[48:51], off nt
	s_nop 1
	v_mov_b32_e32 v48, v60
	v_mov_b32_e32 v49, v52
	v_mov_b32_e32 v52, v61
	v_pk_mul_f32 v[48:49], v[70:71], v[48:49] op_sel_hi:[0,1]
	v_pk_mul_f32 v[50:51], v[70:71], v[52:53] op_sel_hi:[0,1]
	v_pk_mul_f32 v[50:51], v[10:11], v[50:51]
	v_pk_mul_f32 v[48:49], v[8:9], v[48:49]
	global_store_dwordx4 v[54:55], v[48:51], off offset:1024 nt
	s_nop 1
	v_pk_mul_f32 v[48:49], v[70:71], v[62:63] op_sel_hi:[0,1]
	v_pk_mul_f32 v[50:51], v[70:71], v[64:65] op_sel_hi:[0,1]
	v_pk_mul_f32 v[50:51], v[14:15], v[50:51]
	v_pk_mul_f32 v[48:49], v[12:13], v[48:49]
	global_store_dwordx4 v[54:55], v[48:51], off offset:2048 nt
	s_nop 1
	v_pk_mul_f32 v[48:49], v[70:71], v[66:67] op_sel_hi:[0,1]
	v_pk_mul_f32 v[50:51], v[70:71], v[68:69] op_sel_hi:[0,1]
	v_pk_mul_f32 v[50:51], v[18:19], v[50:51]
	v_pk_mul_f32 v[48:49], v[16:17], v[48:49]
	global_store_dwordx4 v[54:55], v[48:51], off offset:3072 nt
	s_and_saveexec_b64 s[18:19], s[6:7]
	s_cbranch_execz .LBB0_916
	s_mul_i32 s0, s75, 24
	v_add_u32_e32 v54, s0, v46
	v_cmp_gt_i32_e64 s[6:7], s70, v54
	v_mov_b32_e32 v46, v44
	v_mov_b32_e32 v47, v45
	v_mov_b32_e32 v48, v42
	v_mov_b32_e32 v49, v43
	v_mov_b32_e32 v50, v32
	v_mov_b32_e32 v51, v33
	v_mov_b32_e32 v52, v30
	v_mov_b32_e32 v53, v31
	s_and_saveexec_b64 s[20:21], s[6:7]
	s_cbranch_execz .LBB0_915
	v_ashrrev_i32_e32 v55, 31, v54
	v_lshlrev_b64 v[46:47], 12, v[54:55]
	v_lshl_add_u64 v[52:53], v[20:21], 0, v[46:47]
	global_load_dwordx2 v[46:47], v[52:53], off
	global_load_dwordx2 v[48:49], v[52:53], off offset:512
	global_load_dwordx2 v[50:51], v[52:53], off offset:1024
	s_nop 0
	global_load_dwordx2 v[52:53], v[52:53], off offset:1536
	s_branch .LBB0_915
